# k2 diff-unit epilogue: 16 sub-layer-norm gain loads issued together instead of a serial load/wait/store chain
# speedup vs baseline: 1.0009x; 1.0009x over previous
.LBB2_1:
	s_mov_b64 s[16:17], s[40:41]
	s_load_dwordx2 s[12:13], s[4:5], 0x78
	s_load_dwordx8 s[4:11], s[16:17], 0x58
	v_lshlrev_b32_e32 v72, 2, v242
	v_xor_b32_e32 v74, 1, v239
	s_waitcnt lgkmcnt(0)
	global_load_dword v68, v72, s[4:5]
	global_load_dword v69, v72, s[6:7]
	global_load_dword v73, v72, s[8:9]
	global_load_dword v76, v72, s[10:11]
	v_xor_b32_e32 v75, 2, v239
	v_cmp_lt_i32_e32 vcc, v74, v67
	v_xor_b32_e32 v77, 4, v239
	v_xor_b32_e32 v78, 8, v239
	v_cndmask_b32_e32 v80, v239, v74, vcc
	v_cmp_lt_i32_e32 vcc, v75, v67
	v_xor_b32_e32 v79, 16, v239
	s_mov_b32 s4, 0x3fb8aa3b
	v_cndmask_b32_e32 v81, v239, v75, vcc
	v_cmp_lt_i32_e32 vcc, v77, v67
	v_lshlrev_b32_e32 v81, 2, v81
	s_waitcnt vmcnt(4)
	ds_read2st64_b32 v[132:133], v66 offset1:1
	ds_read2st64_b32 v[134:135], v66 offset0:2 offset1:3
	ds_read2st64_b32 v[74:75], v66 offset0:4 offset1:5
	ds_read2st64_b32 v[130:131], v66 offset0:6 offset1:7
	ds_read2st64_b32 v[126:127], v66 offset0:8 offset1:9
	ds_read2st64_b32 v[128:129], v66 offset0:10 offset1:11
	ds_read2st64_b32 v[120:121], v66 offset0:12 offset1:13
	ds_read2st64_b32 v[124:125], v66 offset0:14 offset1:15
	v_cndmask_b32_e32 v77, v239, v77, vcc
	v_cmp_lt_i32_e32 vcc, v78, v67
	ds_read2st64_b32 v[118:119], v66 offset0:16 offset1:17
	ds_read2st64_b32 v[122:123], v66 offset0:18 offset1:19
	ds_read2st64_b32 v[112:113], v66 offset0:20 offset1:21
	ds_read2st64_b32 v[116:117], v66 offset0:22 offset1:23
	v_cndmask_b32_e32 v78, v239, v78, vcc
	v_cmp_lt_i32_e32 vcc, v79, v67
	ds_read2st64_b32 v[110:111], v66 offset0:24 offset1:25
	ds_read2st64_b32 v[114:115], v66 offset0:26 offset1:27
	ds_read2st64_b32 v[104:105], v66 offset0:28 offset1:29
	ds_read2st64_b32 v[108:109], v66 offset0:30 offset1:31
	v_cndmask_b32_e32 v67, v239, v79, vcc
	v_lshlrev_b32_e32 v79, 2, v80
	v_lshlrev_b32_e32 v67, 2, v67
	ds_read2st64_b32 v[102:103], v66 offset0:32 offset1:33
	ds_read2st64_b32 v[106:107], v66 offset0:34 offset1:35
	ds_read2st64_b32 v[94:95], v66 offset0:36 offset1:37
	ds_read2st64_b32 v[100:101], v66 offset0:38 offset1:39
	ds_read2st64_b32 v[92:93], v66 offset0:40 offset1:41
	ds_read2st64_b32 v[96:97], v66 offset0:42 offset1:43
	ds_read2st64_b32 v[86:87], v66 offset0:44 offset1:45
	ds_read2st64_b32 v[90:91], v66 offset0:46 offset1:47
	v_lshlrev_b32_e32 v142, 2, v183
	s_add_u32 s0, s0, s14
	s_addc_u32 s1, s1, s15
	s_lshl_b32 s2, s33, 8
	s_and_b32 s2, s2, 0x300
	s_add_u32 s0, s0, s2
	s_mov_b32 s2, 0x800000
	v_or_b32_e32 v72, s24, v241
	s_addc_u32 s1, s1, 0
	s_waitcnt vmcnt(2)
	v_mul_f32_e32 v80, v68, v69
	ds_bpermute_b32 v80, v79, v80
	s_waitcnt vmcnt(0)
	v_mul_f32_e32 v82, v73, v76
	ds_bpermute_b32 v79, v79, v82
	s_waitcnt lgkmcnt(1)
	v_fmac_f32_e32 v80, v68, v69
	ds_bpermute_b32 v68, v81, v80
	s_waitcnt lgkmcnt(1)
	v_fmac_f32_e32 v79, v73, v76
	ds_bpermute_b32 v69, v81, v79
	v_lshlrev_b32_e32 v73, 2, v77
	v_lshlrev_b32_e32 v77, 2, v78
	s_waitcnt lgkmcnt(1)
	v_add_f32_e32 v68, v80, v68
	ds_bpermute_b32 v76, v73, v68
	s_waitcnt lgkmcnt(1)
	v_add_f32_e32 v69, v79, v69
	ds_bpermute_b32 v73, v73, v69
	ds_read2st64_b32 v[84:85], v66 offset0:48 offset1:49
	ds_read2st64_b32 v[88:89], v66 offset0:50 offset1:51
	ds_read2st64_b32 v[80:81], v66 offset0:52 offset1:53
	ds_read2st64_b32 v[82:83], v66 offset0:54 offset1:55
	s_waitcnt lgkmcnt(5)
	v_add_f32_e32 v68, v68, v76
	s_waitcnt lgkmcnt(4)
	v_add_f32_e32 v69, v69, v73
	ds_bpermute_b32 v73, v77, v68
	ds_bpermute_b32 v76, v77, v69
	s_waitcnt lgkmcnt(1)
	v_add_f32_e32 v68, v68, v73
	s_waitcnt lgkmcnt(0)
	v_add_f32_e32 v69, v69, v76
	ds_bpermute_b32 v73, v67, v68
	ds_bpermute_b32 v67, v67, v69
	ds_read2st64_b32 v[76:77], v66 offset0:56 offset1:57
	ds_read2st64_b32 v[78:79], v66 offset0:58 offset1:59
	ds_read2st64_b32 v[138:139], v66 offset0:60 offset1:61
	ds_read2st64_b32 v[136:137], v66 offset0:62 offset1:63
	s_waitcnt lgkmcnt(5)
	v_add_f32_e32 v68, v68, v73
	s_waitcnt lgkmcnt(4)
	v_add_f32_e32 v67, v69, v67
	ds_bpermute_b32 v69, v71, v68
	ds_bpermute_b32 v73, v71, v67
	s_waitcnt lgkmcnt(1)
	v_add_f32_e32 v98, v68, v69
	s_waitcnt lgkmcnt(0)
	v_add_f32_e32 v73, v67, v73
	v_mul_f32_e32 v66, 0x3fb8aa3b, v98
	v_mul_f32_e32 v67, 0x3fb8aa3b, v73
	v_fma_f32 v68, v98, s4, -v66
	v_rndne_f32_e32 v69, v66
	v_fma_f32 v140, v73, s4, -v67
	v_rndne_f32_e32 v141, v67
	v_fmac_f32_e32 v68, 0x32a5705f, v98
	v_sub_f32_e32 v66, v66, v69
	v_fmac_f32_e32 v140, 0x32a5705f, v73
	v_sub_f32_e32 v67, v67, v141
	v_add_f32_e32 v66, v66, v68
	v_cvt_i32_f32_e32 v143, v69
	v_add_f32_e32 v67, v67, v140
	v_exp_f32_e32 v140, v66
	v_cvt_i32_f32_e32 v141, v141
	v_exp_f32_e32 v144, v67
	s_mov_b32 s4, 0xc2ce8ed0
	v_ldexp_f32 v140, v140, v143
	v_cmp_ngt_f32_e32 vcc, s4, v98
	v_ldexp_f32 v141, v144, v141
	global_load_dwordx4 v[66:69], v142, s[12:13]
	v_cndmask_b32_e32 v140, 0, v140, vcc
	v_cmp_ngt_f32_e32 vcc, s4, v73
	s_mov_b32 s4, 0x42b17218
	s_nop 0
	v_cndmask_b32_e32 v141, 0, v141, vcc
	v_cmp_nlt_f32_e32 vcc, s4, v98
	s_nop 1
	v_cndmask_b32_e32 v98, v240, v140, vcc
	v_cmp_nlt_f32_e32 vcc, s4, v73
	s_nop 1
	v_cndmask_b32_e32 v73, v240, v141, vcc
	v_sub_f32_e32 v73, v98, v73
	v_add_f32_e32 v98, 0x3e4ccccd, v73
	v_pk_mul_f32 v[138:139], v[98:99], v[138:139] op_sel_hi:[0,1]
	v_pk_mul_f32 v[136:137], v[98:99], v[136:137] op_sel_hi:[0,1]
	v_pk_mul_f32 v[144:145], v[98:99], v[74:75] op_sel_hi:[0,1]
	v_pk_fma_f32 v[74:75], v[14:15], v[70:71], v[138:139] op_sel_hi:[1,0,1] neg_lo:[0,0,1] neg_hi:[0,0,1]
	v_pk_fma_f32 v[14:15], v[16:17], v[70:71], v[136:137] op_sel_hi:[1,0,1] neg_lo:[0,0,1] neg_hi:[0,0,1]
	v_pk_mul_f32 v[16:17], v[98:99], v[128:129] op_sel_hi:[0,1]
	v_pk_fma_f32 v[128:129], v[44:45], v[70:71], v[16:17] op_sel_hi:[1,0,1] neg_lo:[0,0,1] neg_hi:[0,0,1]
	v_pk_mul_f32 v[16:17], v[98:99], v[126:127] op_sel_hi:[0,1]
	v_pk_fma_f32 v[126:127], v[42:43], v[70:71], v[16:17] op_sel_hi:[1,0,1] neg_lo:[0,0,1] neg_hi:[0,0,1]
	v_pk_mul_f32 v[16:17], v[98:99], v[124:125] op_sel_hi:[0,1]
	v_pk_fma_f32 v[124:125], v[48:49], v[70:71], v[16:17] op_sel_hi:[1,0,1] neg_lo:[0,0,1] neg_hi:[0,0,1]
	v_pk_mul_f32 v[16:17], v[98:99], v[120:121] op_sel_hi:[0,1]
	v_pk_fma_f32 v[120:121], v[46:47], v[70:71], v[16:17] op_sel_hi:[1,0,1] neg_lo:[0,0,1] neg_hi:[0,0,1]
	v_pk_mul_f32 v[16:17], v[98:99], v[122:123] op_sel_hi:[0,1]
	v_pk_fma_f32 v[52:53], v[52:53], v[70:71], v[16:17] op_sel_hi:[1,0,1] neg_lo:[0,0,1] neg_hi:[0,0,1]
	v_pk_mul_f32 v[16:17], v[98:99], v[118:119] op_sel_hi:[0,1]
	v_pk_fma_f32 v[118:119], v[50:51], v[70:71], v[16:17] op_sel_hi:[1,0,1] neg_lo:[0,0,1] neg_hi:[0,0,1]
	v_pk_mul_f32 v[16:17], v[98:99], v[116:117] op_sel_hi:[0,1]
	v_pk_fma_f32 v[48:49], v[56:57], v[70:71], v[16:17] op_sel_hi:[1,0,1] neg_lo:[0,0,1] neg_hi:[0,0,1]
	v_pk_mul_f32 v[16:17], v[98:99], v[112:113] op_sel_hi:[0,1]
	v_pk_fma_f32 v[54:55], v[54:55], v[70:71], v[16:17] op_sel_hi:[1,0,1] neg_lo:[0,0,1] neg_hi:[0,0,1]
	v_pk_mul_f32 v[16:17], v[98:99], v[114:115] op_sel_hi:[0,1]
	v_pk_fma_f32 v[44:45], v[60:61], v[70:71], v[16:17] op_sel_hi:[1,0,1] neg_lo:[0,0,1] neg_hi:[0,0,1]
	v_pk_mul_f32 v[16:17], v[98:99], v[110:111] op_sel_hi:[0,1]
	v_pk_mul_f32 v[130:131], v[98:99], v[130:131] op_sel_hi:[0,1]
	v_pk_fma_f32 v[50:51], v[58:59], v[70:71], v[16:17] op_sel_hi:[1,0,1] neg_lo:[0,0,1] neg_hi:[0,0,1]
	v_pk_mul_f32 v[16:17], v[98:99], v[108:109] op_sel_hi:[0,1]
	v_pk_fma_f32 v[130:131], v[40:41], v[70:71], v[130:131] op_sel_hi:[1,0,1] neg_lo:[0,0,1] neg_hi:[0,0,1]
	v_pk_fma_f32 v[40:41], v[64:65], v[70:71], v[16:17] op_sel_hi:[1,0,1] neg_lo:[0,0,1] neg_hi:[0,0,1]
	v_pk_mul_f32 v[16:17], v[98:99], v[104:105] op_sel_hi:[0,1]
	v_pk_mul_f32 v[134:135], v[134:135], v[98:99] op_sel_hi:[1,0]
	v_pk_fma_f32 v[46:47], v[62:63], v[70:71], v[16:17] op_sel_hi:[1,0,1] neg_lo:[0,0,1] neg_hi:[0,0,1]
	v_pk_mul_f32 v[16:17], v[98:99], v[106:107] op_sel_hi:[0,1]
	v_pk_mul_f32 v[140:141], v[132:133], v[98:99] op_sel_hi:[1,0]
	v_pk_fma_f32 v[132:133], v[36:37], v[70:71], v[134:135] op_sel_hi:[1,0,1] neg_lo:[0,0,1] neg_hi:[0,0,1]
	v_pk_fma_f32 v[36:37], v[20:21], v[70:71], v[16:17] op_sel_hi:[1,0,1] neg_lo:[0,0,1] neg_hi:[0,0,1]
	v_pk_mul_f32 v[16:17], v[98:99], v[102:103] op_sel_hi:[0,1]
	v_pk_fma_f32 v[42:43], v[18:19], v[70:71], v[16:17] op_sel_hi:[1,0,1] neg_lo:[0,0,1] neg_hi:[0,0,1]
	v_pk_mul_f32 v[16:17], v[98:99], v[100:101] op_sel_hi:[0,1]
	v_pk_fma_f32 v[136:137], v[34:35], v[70:71], v[140:141] op_sel_hi:[1,0,1] neg_lo:[0,0,1] neg_hi:[0,0,1]
	v_pk_fma_f32 v[34:35], v[24:25], v[70:71], v[16:17] op_sel_hi:[1,0,1] neg_lo:[0,0,1] neg_hi:[0,0,1]
	v_pk_mul_f32 v[16:17], v[98:99], v[94:95] op_sel_hi:[0,1]
	v_pk_fma_f32 v[134:135], v[38:39], v[70:71], v[144:145] op_sel_hi:[1,0,1] neg_lo:[0,0,1] neg_hi:[0,0,1]
	v_pk_fma_f32 v[38:39], v[22:23], v[70:71], v[16:17] op_sel_hi:[1,0,1] neg_lo:[0,0,1] neg_hi:[0,0,1]
	v_pk_mul_f32 v[16:17], v[98:99], v[96:97] op_sel_hi:[0,1]
	v_pk_fma_f32 v[22:23], v[28:29], v[70:71], v[16:17] op_sel_hi:[1,0,1] neg_lo:[0,0,1] neg_hi:[0,0,1]
	v_pk_mul_f32 v[16:17], v[98:99], v[92:93] op_sel_hi:[0,1]
	v_pk_fma_f32 v[26:27], v[26:27], v[70:71], v[16:17] op_sel_hi:[1,0,1] neg_lo:[0,0,1] neg_hi:[0,0,1]
	v_pk_mul_f32 v[16:17], v[98:99], v[90:91] op_sel_hi:[0,1]
	v_pk_fma_f32 v[18:19], v[32:33], v[70:71], v[16:17] op_sel_hi:[1,0,1] neg_lo:[0,0,1] neg_hi:[0,0,1]
	v_pk_mul_f32 v[16:17], v[98:99], v[86:87] op_sel_hi:[0,1]
	v_pk_fma_f32 v[24:25], v[30:31], v[70:71], v[16:17] op_sel_hi:[1,0,1] neg_lo:[0,0,1] neg_hi:[0,0,1]
	v_pk_mul_f32 v[16:17], v[98:99], v[88:89] op_sel_hi:[0,1]
	v_pk_fma_f32 v[16:17], v[4:5], v[70:71], v[16:17] op_sel_hi:[1,0,1] neg_lo:[0,0,1] neg_hi:[0,0,1]
	v_pk_mul_f32 v[4:5], v[98:99], v[84:85] op_sel_hi:[0,1]
	v_pk_fma_f32 v[20:21], v[2:3], v[70:71], v[4:5] op_sel_hi:[1,0,1] neg_lo:[0,0,1] neg_hi:[0,0,1]
	v_pk_mul_f32 v[2:3], v[98:99], v[82:83] op_sel_hi:[0,1]
	v_pk_fma_f32 v[4:5], v[8:9], v[70:71], v[2:3] op_sel_hi:[1,0,1] neg_lo:[0,0,1] neg_hi:[0,0,1]
	v_pk_mul_f32 v[2:3], v[98:99], v[80:81] op_sel_hi:[0,1]
	v_pk_mul_f32 v[146:147], v[136:137], v[136:137]
	v_pk_fma_f32 v[8:9], v[6:7], v[70:71], v[2:3] op_sel_hi:[1,0,1] neg_lo:[0,0,1] neg_hi:[0,0,1]
	v_pk_mul_f32 v[2:3], v[98:99], v[78:79] op_sel_hi:[0,1]
	v_pk_mul_f32 v[6:7], v[98:99], v[76:77] op_sel_hi:[0,1]
	v_pk_mul_f32 v[144:145], v[132:133], v[132:133]
	v_pk_fma_f32 v[2:3], v[12:13], v[70:71], v[2:3] op_sel_hi:[1,0,1] neg_lo:[0,0,1] neg_hi:[0,0,1]
	v_pk_fma_f32 v[6:7], v[10:11], v[70:71], v[6:7] op_sel_hi:[1,0,1] neg_lo:[0,0,1] neg_hi:[0,0,1]
	v_add_f32_e32 v70, v146, v147
	v_add_f32_e32 v70, v144, v70
	v_pk_mul_f32 v[150:151], v[134:135], v[134:135]
	v_add_f32_e32 v70, v145, v70
	v_add_f32_e32 v70, v150, v70
	v_pk_mul_f32 v[148:149], v[130:131], v[130:131]
	v_add_f32_e32 v70, v151, v70
	v_add_f32_e32 v70, v148, v70
	v_pk_mul_f32 v[154:155], v[126:127], v[126:127]
	v_add_f32_e32 v70, v149, v70
	v_add_f32_e32 v70, v154, v70
	v_pk_mul_f32 v[152:153], v[128:129], v[128:129]
	v_add_f32_e32 v70, v155, v70
	v_add_f32_e32 v70, v152, v70
	v_pk_mul_f32 v[158:159], v[120:121], v[120:121]
	v_add_f32_e32 v70, v153, v70
	v_add_f32_e32 v70, v158, v70
	v_pk_mul_f32 v[156:157], v[124:125], v[124:125]
	v_add_f32_e32 v70, v159, v70
	v_add_f32_e32 v70, v156, v70
	v_pk_mul_f32 v[160:161], v[118:119], v[118:119]
	v_add_f32_e32 v70, v157, v70
	v_add_f32_e32 v70, v160, v70
	v_pk_mul_f32 v[122:123], v[52:53], v[52:53]
	v_add_f32_e32 v70, v161, v70
	v_add_f32_e32 v70, v122, v70
	v_pk_mul_f32 v[112:113], v[54:55], v[54:55]
	v_add_f32_e32 v70, v123, v70
	v_add_f32_e32 v70, v112, v70
	v_pk_mul_f32 v[56:57], v[48:49], v[48:49]
	v_add_f32_e32 v70, v113, v70
	v_add_f32_e32 v56, v56, v70
	v_pk_mul_f32 v[58:59], v[50:51], v[50:51]
	v_add_f32_e32 v56, v57, v56
	v_add_f32_e32 v56, v58, v56
	v_pk_mul_f32 v[60:61], v[44:45], v[44:45]
	v_add_f32_e32 v56, v59, v56
	v_add_f32_e32 v56, v60, v56
	v_pk_mul_f32 v[62:63], v[46:47], v[46:47]
	v_add_f32_e32 v56, v61, v56
	v_add_f32_e32 v56, v62, v56
	v_pk_mul_f32 v[64:65], v[40:41], v[40:41]
	v_add_f32_e32 v56, v63, v56
	v_add_f32_e32 v56, v64, v56
	v_pk_mul_f32 v[102:103], v[42:43], v[42:43]
	v_add_f32_e32 v56, v65, v56
	v_add_f32_e32 v56, v102, v56
	v_pk_mul_f32 v[104:105], v[36:37], v[36:37]
	v_add_f32_e32 v56, v103, v56
	v_add_f32_e32 v56, v104, v56
	v_pk_mul_f32 v[94:95], v[38:39], v[38:39]
	v_add_f32_e32 v56, v105, v56
	v_add_f32_e32 v56, v94, v56
	v_pk_mul_f32 v[100:101], v[34:35], v[34:35]
	v_add_f32_e32 v56, v95, v56
	v_add_f32_e32 v56, v100, v56
	v_pk_mul_f32 v[92:93], v[26:27], v[26:27]
	v_add_f32_e32 v56, v101, v56
	v_add_f32_e32 v56, v92, v56
	v_pk_mul_f32 v[28:29], v[22:23], v[22:23]
	v_add_f32_e32 v56, v93, v56
	v_add_f32_e32 v28, v28, v56
	v_pk_mul_f32 v[30:31], v[24:25], v[24:25]
	v_add_f32_e32 v28, v29, v28
	v_add_f32_e32 v28, v30, v28
	v_pk_mul_f32 v[32:33], v[18:19], v[18:19]
	v_add_f32_e32 v28, v31, v28
	v_add_f32_e32 v28, v32, v28
	v_pk_mul_f32 v[84:85], v[20:21], v[20:21]
	v_add_f32_e32 v28, v33, v28
	v_add_f32_e32 v28, v84, v28
	v_pk_mul_f32 v[86:87], v[16:17], v[16:17]
	v_add_f32_e32 v28, v85, v28
	v_add_f32_e32 v28, v86, v28
	v_pk_mul_f32 v[80:81], v[8:9], v[8:9]
	v_add_f32_e32 v28, v87, v28
	v_add_f32_e32 v28, v80, v28
	v_pk_mul_f32 v[82:83], v[4:5], v[4:5]
	v_add_f32_e32 v28, v81, v28
	v_add_f32_e32 v28, v82, v28
	v_pk_mul_f32 v[10:11], v[6:7], v[6:7]
	v_add_f32_e32 v28, v83, v28
	v_add_f32_e32 v10, v10, v28
	v_pk_mul_f32 v[12:13], v[2:3], v[2:3]
	v_add_f32_e32 v10, v11, v10
	v_add_f32_e32 v10, v12, v10
	v_pk_mul_f32 v[140:141], v[74:75], v[74:75]
	v_add_f32_e32 v10, v13, v10
	v_add_f32_e32 v10, v140, v10
	v_pk_mul_f32 v[138:139], v[14:15], v[14:15]
	v_add_f32_e32 v10, v141, v10
	v_add_f32_e32 v10, v138, v10
	v_add_f32_e32 v12, v139, v10
	global_load_dwordx4 v[56:59], v142, s[12:13] offset:32
	global_load_dwordx4 v[60:63], v142, s[12:13] offset:64
	global_load_dwordx4 v[76:79], v142, s[12:13] offset:96
	global_load_dwordx4 v[80:83], v142, s[12:13] offset:128
	global_load_dwordx4 v[84:87], v142, s[12:13] offset:160
	global_load_dwordx4 v[88:91], v142, s[12:13] offset:192
	global_load_dwordx4 v[92:95], v142, s[12:13] offset:224
	global_load_dwordx4 v[100:103], v142, s[12:13] offset:256
	global_load_dwordx4 v[104:107], v142, s[12:13] offset:288
	global_load_dwordx4 v[108:111], v142, s[12:13] offset:320
	global_load_dwordx4 v[112:115], v142, s[12:13] offset:352
	global_load_dwordx4 v[144:147], v142, s[12:13] offset:384
	global_load_dwordx4 v[148:151], v142, s[12:13] offset:416
	global_load_dwordx4 v[152:155], v142, s[12:13] offset:448
	global_load_dwordx4 v[156:159], v142, s[12:13] offset:480
	ds_bpermute_b32 v13, v71, v12
	v_ashrrev_i32_e32 v73, 31, v72
	v_lshlrev_b64 v[10:11], 11, v[72:73]
	v_lshl_add_u64 v[10:11], s[0:1], 0, v[10:11]
	v_lshlrev_b32_e32 v98, 1, v183
	s_waitcnt lgkmcnt(0)
	v_add_f32_e32 v12, v12, v13
	v_fmamk_f32 v12, v12, 0x3c000000, v237
	v_mul_f32_e32 v13, 0x4b800000, v12
	v_cmp_gt_f32_e32 vcc, s2, v12
	s_mov_b64 s[0:1], 0xd700000
	s_nop 0
	v_cndmask_b32_e32 v12, v12, v13, vcc
	v_rsq_f32_e32 v28, v12
	v_lshl_add_u64 v[12:13], v[10:11], 0, v[98:99]
	v_mul_f32_e32 v10, 0x45800000, v28
	v_cndmask_b32_e32 v10, v28, v10, vcc
	v_mul_f32_e32 v10, 0x3f4ccccd, v10
	v_lshl_add_u64 v[12:13], v[12:13], 0, s[0:1]
	s_waitcnt vmcnt(15)
	v_pk_mul_f32 v[28:29], v[136:137], v[10:11] op_sel_hi:[1,0]
	v_pk_mul_f32 v[30:31], v[132:133], v[10:11] op_sel_hi:[1,0]
	v_pk_mul_f32 v[28:29], v[66:67], v[28:29]
	v_pk_mul_f32 v[30:31], v[68:69], v[30:31]
	v_cvt_pk_bf16_f32 v66, v28, v29
	v_cvt_pk_bf16_f32 v67, v30, v31
	s_waitcnt vmcnt(14)
	v_pk_mul_f32 v[28:29], v[134:135], v[10:11] op_sel_hi:[1,0]
	v_pk_mul_f32 v[30:31], v[130:131], v[10:11] op_sel_hi:[1,0]
	v_pk_mul_f32 v[28:29], v[56:57], v[28:29]
	v_pk_mul_f32 v[30:31], v[58:59], v[30:31]
	v_cvt_pk_bf16_f32 v56, v28, v29
	v_cvt_pk_bf16_f32 v57, v30, v31
	s_waitcnt vmcnt(13)
	v_pk_mul_f32 v[28:29], v[126:127], v[10:11] op_sel_hi:[1,0]
	v_pk_mul_f32 v[30:31], v[128:129], v[10:11] op_sel_hi:[1,0]
	v_pk_mul_f32 v[28:29], v[60:61], v[28:29]
	v_pk_mul_f32 v[30:31], v[62:63], v[30:31]
	v_cvt_pk_bf16_f32 v60, v28, v29
	v_cvt_pk_bf16_f32 v61, v30, v31
	s_waitcnt vmcnt(12)
	v_pk_mul_f32 v[28:29], v[120:121], v[10:11] op_sel_hi:[1,0]
	v_pk_mul_f32 v[30:31], v[124:125], v[10:11] op_sel_hi:[1,0]
	v_pk_mul_f32 v[28:29], v[76:77], v[28:29]
	v_pk_mul_f32 v[30:31], v[78:79], v[30:31]
	v_cvt_pk_bf16_f32 v76, v28, v29
	v_cvt_pk_bf16_f32 v77, v30, v31
	s_waitcnt vmcnt(11)
	v_pk_mul_f32 v[28:29], v[118:119], v[10:11] op_sel_hi:[1,0]
	v_pk_mul_f32 v[30:31], v[52:53], v[10:11] op_sel_hi:[1,0]
	v_pk_mul_f32 v[28:29], v[80:81], v[28:29]
	v_pk_mul_f32 v[30:31], v[82:83], v[30:31]
	v_cvt_pk_bf16_f32 v80, v28, v29
	v_cvt_pk_bf16_f32 v81, v30, v31
	s_waitcnt vmcnt(10)
	v_pk_mul_f32 v[28:29], v[54:55], v[10:11] op_sel_hi:[1,0]
	v_pk_mul_f32 v[30:31], v[48:49], v[10:11] op_sel_hi:[1,0]
	v_pk_mul_f32 v[28:29], v[84:85], v[28:29]
	v_pk_mul_f32 v[30:31], v[86:87], v[30:31]
	v_cvt_pk_bf16_f32 v84, v28, v29
	v_cvt_pk_bf16_f32 v85, v30, v31
	s_waitcnt vmcnt(9)
	v_pk_mul_f32 v[28:29], v[50:51], v[10:11] op_sel_hi:[1,0]
	v_pk_mul_f32 v[30:31], v[44:45], v[10:11] op_sel_hi:[1,0]
	v_pk_mul_f32 v[28:29], v[88:89], v[28:29]
	v_pk_mul_f32 v[30:31], v[90:91], v[30:31]
	v_cvt_pk_bf16_f32 v88, v28, v29
	v_cvt_pk_bf16_f32 v89, v30, v31
	s_waitcnt vmcnt(8)
	v_pk_mul_f32 v[28:29], v[46:47], v[10:11] op_sel_hi:[1,0]
	v_pk_mul_f32 v[30:31], v[40:41], v[10:11] op_sel_hi:[1,0]
	v_pk_mul_f32 v[28:29], v[92:93], v[28:29]
	v_pk_mul_f32 v[30:31], v[94:95], v[30:31]
	v_cvt_pk_bf16_f32 v92, v28, v29
	v_cvt_pk_bf16_f32 v93, v30, v31
	s_waitcnt vmcnt(7)
	v_pk_mul_f32 v[28:29], v[42:43], v[10:11] op_sel_hi:[1,0]
	v_pk_mul_f32 v[30:31], v[36:37], v[10:11] op_sel_hi:[1,0]
	v_pk_mul_f32 v[28:29], v[100:101], v[28:29]
	v_pk_mul_f32 v[30:31], v[102:103], v[30:31]
	v_cvt_pk_bf16_f32 v100, v28, v29
	v_cvt_pk_bf16_f32 v101, v30, v31
	s_waitcnt vmcnt(6)
	v_pk_mul_f32 v[28:29], v[38:39], v[10:11] op_sel_hi:[1,0]
	v_pk_mul_f32 v[30:31], v[34:35], v[10:11] op_sel_hi:[1,0]
	v_pk_mul_f32 v[28:29], v[104:105], v[28:29]
	v_pk_mul_f32 v[30:31], v[106:107], v[30:31]
	v_cvt_pk_bf16_f32 v104, v28, v29
	v_cvt_pk_bf16_f32 v105, v30, v31
	s_waitcnt vmcnt(5)
	v_pk_mul_f32 v[28:29], v[26:27], v[10:11] op_sel_hi:[1,0]
	v_pk_mul_f32 v[30:31], v[22:23], v[10:11] op_sel_hi:[1,0]
	v_pk_mul_f32 v[28:29], v[108:109], v[28:29]
	v_pk_mul_f32 v[30:31], v[110:111], v[30:31]
	v_cvt_pk_bf16_f32 v108, v28, v29
	v_cvt_pk_bf16_f32 v109, v30, v31
	s_waitcnt vmcnt(4)
	v_pk_mul_f32 v[28:29], v[24:25], v[10:11] op_sel_hi:[1,0]
	v_pk_mul_f32 v[30:31], v[18:19], v[10:11] op_sel_hi:[1,0]
	v_pk_mul_f32 v[28:29], v[112:113], v[28:29]
	v_pk_mul_f32 v[30:31], v[114:115], v[30:31]
	v_cvt_pk_bf16_f32 v112, v28, v29
	v_cvt_pk_bf16_f32 v113, v30, v31
	s_waitcnt vmcnt(3)
	v_pk_mul_f32 v[28:29], v[20:21], v[10:11] op_sel_hi:[1,0]
	v_pk_mul_f32 v[30:31], v[16:17], v[10:11] op_sel_hi:[1,0]
	v_pk_mul_f32 v[28:29], v[144:145], v[28:29]
	v_pk_mul_f32 v[30:31], v[146:147], v[30:31]
	v_cvt_pk_bf16_f32 v144, v28, v29
	v_cvt_pk_bf16_f32 v145, v30, v31
	s_waitcnt vmcnt(2)
	v_pk_mul_f32 v[28:29], v[8:9], v[10:11] op_sel_hi:[1,0]
	v_pk_mul_f32 v[30:31], v[4:5], v[10:11] op_sel_hi:[1,0]
	v_pk_mul_f32 v[28:29], v[148:149], v[28:29]
	v_pk_mul_f32 v[30:31], v[150:151], v[30:31]
	v_cvt_pk_bf16_f32 v148, v28, v29
	v_cvt_pk_bf16_f32 v149, v30, v31
	s_waitcnt vmcnt(1)
	v_pk_mul_f32 v[28:29], v[6:7], v[10:11] op_sel_hi:[1,0]
	v_pk_mul_f32 v[30:31], v[2:3], v[10:11] op_sel_hi:[1,0]
	v_pk_mul_f32 v[28:29], v[152:153], v[28:29]
	v_pk_mul_f32 v[30:31], v[154:155], v[30:31]
	v_cvt_pk_bf16_f32 v152, v28, v29
	v_cvt_pk_bf16_f32 v153, v30, v31
	s_waitcnt vmcnt(0)
	v_pk_mul_f32 v[28:29], v[74:75], v[10:11] op_sel_hi:[1,0]
	v_pk_mul_f32 v[30:31], v[14:15], v[10:11] op_sel_hi:[1,0]
	v_pk_mul_f32 v[28:29], v[156:157], v[28:29]
	v_pk_mul_f32 v[30:31], v[158:159], v[30:31]
	v_cvt_pk_bf16_f32 v156, v28, v29
	v_cvt_pk_bf16_f32 v157, v30, v31
	global_store_dwordx2 v[12:13], v[66:67], off
	global_store_dwordx2 v[12:13], v[56:57], off offset:16
	global_store_dwordx2 v[12:13], v[60:61], off offset:32
	global_store_dwordx2 v[12:13], v[76:77], off offset:48
	global_store_dwordx2 v[12:13], v[80:81], off offset:64
	global_store_dwordx2 v[12:13], v[84:85], off offset:80
	global_store_dwordx2 v[12:13], v[88:89], off offset:96
	global_store_dwordx2 v[12:13], v[92:93], off offset:112
	global_store_dwordx2 v[12:13], v[100:101], off offset:128
	global_store_dwordx2 v[12:13], v[104:105], off offset:144
	global_store_dwordx2 v[12:13], v[108:109], off offset:160
	global_store_dwordx2 v[12:13], v[112:113], off offset:176
	global_store_dwordx2 v[12:13], v[144:145], off offset:192
	global_store_dwordx2 v[12:13], v[148:149], off offset:208
	global_store_dwordx2 v[12:13], v[152:153], off offset:224
	global_store_dwordx2 v[12:13], v[156:157], off offset:240
